# GEMM_in main loop: fragment ds_reads moved into MFMA shadows with a second register set (v236-v255) for A1(substep0)/B(substep1); no read waited right after issue
# speedup vs baseline: 1.0053x; 1.0038x over previous
; DI f32x16 mfma32(bf16x8 a, bf16x8 b, f32x16 c) { return __builtin_amdgcn_mfma_f32_32x32x16_bf16(a, b, c, 0, 0, 0); }
; #define RAW_BARRIER() do { asm volatile("s_waitcnt lgkmcnt(0)" ::: "memory"); __builtin_amdgcn_s_barrier(); } while (0)
; DI void gemm_tile(const Params& p, const GemmJob& j, int mt, int nt, char* smem) {
;     ...
;   auto glds = [&](int kt, int stage) {
;     char* sb = smem + stage * GSTAGE;
;     const unsigned ko = j.amode ? (unsigned)((kt >> 1) * j.lda + (kt & 1) * 32) : (unsigned)(kt * 32);
; #pragma unroll
;     for (int q = 0; q < 2; ++q) {
;       const int ch = q * 4 + wid;
;       const bf16_t* src = j.bblk ? j.Bt + ((size_t)kt * j.bblk + n0 + 16 * ch + rl) * 32 + c8s : j.Bt + (size_t)(n0 + 16 * ch + rl) * j.K + kt * 32 + c8s;
;       __builtin_amdgcn_global_load_lds((gptr_t)src, (lptr_t)(sb + ch * 1024), 16, 0, 0);
;     }
; #pragma unroll
;     for (int q = 0; q < 4; ++q) {
;       const int ch = q * 4 + wid;
;       const bf16_t* src = j.ablk ? j.A + ((size_t)kt * j.ablk + t0 + 16 * ch + rl) * 32 + c8s : j.A + a_rowoff(j, t0 + 16 * ch + rl) + ko + c8s;
;       __builtin_amdgcn_global_load_lds((gptr_t)src, (lptr_t)(sb + 8192 + ch * 1024), 16, 0, 0);
;     }
;   };
;   const int fr = (r >> 2) & 3; const int o0 = (h ^ fr) * 16;
;   __syncthreads();
;   glds(0, 0);
;   if (nk > 1) glds(1, 1);
;   int st = 0, st2 = 2;
;   for (int kt = 0; kt < nk; ++kt) {
;     if (kt + 1 < nk) asm volatile("s_waitcnt vmcnt(6)" ::: "memory"); else asm volatile("s_waitcnt vmcnt(0)" ::: "memory");
;     RAW_BARRIER();
;     if (kt + 2 < nk) glds(kt + 2, st2);
;     const char* sb = smem + st * GSTAGE;
; #pragma unroll
;     for (int ks = 0; ks < 2; ++ks) {
;       const int off = ks ? (o0 ^ 32) : o0;
;       bf16x8 wf[2], xf[4];
; #pragma unroll
;       for (int a = 0; a < 2; ++a) wf[a] = *(const bf16x8*)(sb + (64 * wn + 32 * a + r) * 64 + off);
; #pragma unroll
;       for (int b = 0; b < 4; ++b) xf[b] = *(const bf16x8*)(sb + 8192 + (128 * wt + 32 * b + r) * 64 + off);
; #pragma unroll
;       for (int a = 0; a < 2; ++a)
; #pragma unroll
;         for (int b = 0; b < 4; ++b) acc[a][b] = mfma32(wf[a], xf[b], acc[a][b]);
;     }
;     st = (st == 2) ? 0 : st + 1; st2 = (st2 == 2) ? 0 : st2 + 1;
.LBB0_103:
	s_add_i32 s37, s63, s33
	v_lshl_add_u64 v[232:233], v[232:233], 0, v[0:1]
	s_mov_b32 m0, s37
	v_lshl_add_u64 v[134:135], v[134:135], 0, 64
	global_load_lds_dwordx4 v[232:233], off
	v_lshl_add_u64 v[232:233], v[138:139], 0, s[8:9]
	v_lshl_add_u64 v[234:235], v[232:233], 0, s[92:93]
	s_add_i32 m0, s36, 0x2000
	s_add_i32 s36, s63, s55
	global_load_lds_dwordx4 v[234:235], off
	v_lshl_add_u64 v[234:235], v[140:141], 0, s[8:9]
	s_add_i32 m0, s37, 0x2000
	v_lshl_add_u64 v[136:137], v[136:137], 0, 64
	global_load_lds_dwordx4 v[234:235], off
	v_lshl_add_u64 v[234:235], v[232:233], 0, s[84:85]
	s_add_i32 m0, s36, 0x2000
	s_add_i32 s36, s63, s58
	global_load_lds_dwordx4 v[234:235], off
	v_lshl_add_u64 v[232:233], v[232:233], 0, s[52:53]
	s_add_i32 m0, s36, 0x2000
	s_nop 0
	global_load_lds_dwordx4 v[232:233], off
	v_add_u32_e32 v234, s100, v150
	v_add_u32_e32 v235, v234, v149
	v_add_u32_e32 v234, v234, v148
	s_waitcnt lgkmcnt(0)
	v_mfma_f32_32x32x16_bf16 v[114:129], v[152:155], v[156:159], v[114:129]
	ds_read_b128 v[236:239], v143 offset:2048
	s_add_i32 s36, s11, 1
	s_cmp_lg_u32 s11, 2
	s_cselect_b32 s11, s36, 0
	s_add_i32 s36, s70, 1
	s_cmp_lg_u32 s70, 2
	s_cselect_b32 s70, s36, 0
	v_mfma_f32_32x32x16_bf16 v[82:97], v[152:155], v[160:163], v[82:97]
	ds_read_b128 v[240:243], v234 offset:8192
	s_add_u32 s8, s8, 0x200000
	s_addc_u32 s9, s9, 0
	s_add_i32 s62, s62, 1
	s_cmp_eq_u32 s8, 0x3c00000
	v_mfma_f32_32x32x16_bf16 v[50:65], v[152:155], v[180:183], v[50:65]
	ds_read_b128 v[244:247], v234 offset:10240
	v_mfma_f32_32x32x16_bf16 v[18:33], v[152:155], v[184:187], v[18:33]
	ds_read_b128 v[248:251], v234 offset:12288
	s_waitcnt lgkmcnt(3)
	v_mfma_f32_32x32x16_bf16 v[98:113], v[236:239], v[156:159], v[98:113]
	ds_read_b128 v[252:255], v234 offset:14336
	v_mfma_f32_32x32x16_bf16 v[66:81], v[236:239], v[160:163], v[66:81]
	ds_read_b128 v[152:155], v235
	v_mfma_f32_32x32x16_bf16 v[34:49], v[236:239], v[180:183], v[34:49]
	v_mfma_f32_32x32x16_bf16 v[2:17], v[236:239], v[184:187], v[2:17]
	ds_read_b128 v[236:239], v235 offset:2048
	s_waitcnt lgkmcnt(1)
	v_mfma_f32_32x32x16_bf16 v[114:129], v[152:155], v[240:243], v[114:129]
	v_mfma_f32_32x32x16_bf16 v[82:97], v[152:155], v[244:247], v[82:97]
	v_mfma_f32_32x32x16_bf16 v[50:65], v[152:155], v[248:251], v[50:65]
	v_mfma_f32_32x32x16_bf16 v[18:33], v[152:155], v[252:255], v[18:33]
	s_waitcnt lgkmcnt(0)
	v_mfma_f32_32x32x16_bf16 v[98:113], v[236:239], v[240:243], v[98:113]
	v_mfma_f32_32x32x16_bf16 v[66:81], v[236:239], v[244:247], v[66:81]
	v_mfma_f32_32x32x16_bf16 v[34:49], v[236:239], v[248:251], v[34:49]
	v_mfma_f32_32x32x16_bf16 v[2:17], v[236:239], v[252:255], v[2:17]
	s_cbranch_scc1 .LBB0_108
